# v16 + spatial phase MFMA section: LDS operand reads double-buffered one k-step ahead instead of read-wait-mfma
# baseline (speedup 1.0000x reference)
; #define LAS __attribute__((address_space(3)))
; __device__ __forceinline__ unsigned cvt_pk_bf16(float lo, float hi) { f32x2 v = {lo, hi}; bf16x2_t b = __builtin_convertvector(v, bf16x2_t); return __builtin_bit_cast(unsigned, b); }
; __device__ __forceinline__ float bf_lo(unsigned u) { return __uint_as_float(u << 16); }
; __device__ __forceinline__ float bf_hi(unsigned u) { return __uint_as_float(u & 0xffff0000u); }
; __device__ __forceinline__ void phase_spatial(const Args& a, LAS unsigned char* lds, int j, int nchunks) {
;     ...
;             f32x4 g0 = *(const f32x4*)(lng + g * 256 + lch * 8), g1 = *(const f32x4*)(lng + g * 256 + lch * 8 + 4), b0 = *(const f32x4*)(lnb + g * 256 + lch * 8), b1 = *(const f32x4*)(lnb + g * 256 + lch * 8 + 4);
; #pragma unroll
;             for (int p = 0; p < 8; ++p) { const int row = lrow + 16 * p; const u32x4 w = *(const u32x4*)(Z + (row0 + row) * SGUW + SGUH + g * 256 + lch * 8);
;                 const f32x2 ms = *(const f32x2*)(st + 2 * (row0 + row));
;                 f32x4 x0 = {bf_lo(w.x), bf_hi(w.x), bf_lo(w.y), bf_hi(w.y)}, x1 = {bf_lo(w.z), bf_hi(w.z), bf_lo(w.w), bf_hi(w.w)};
;                 x0 = (x0 - ms.x) * ms.y * g0 + b0; x1 = (x1 - ms.x) * ms.y * g1 + b1;
;                 u32x4 o; o.x = cvt_pk_bf16(x0[0], x0[1]); o.y = cvt_pk_bf16(x0[2], x0[3]); o.z = cvt_pk_bf16(x1[0], x1[1]); o.w = cvt_pk_bf16(x1[2], x1[3]);
;                 *(LAS u32x4*)(vt + (lch >> 2) * 8192 + (row >> 3) * 512 + (row & 7) * 64 + (lch & 3) * 16) = o; }
;     ...
;         for (int pb = 0; pb < 4; ++pb) { const int p = 32 * pb + r32; const float bias = bs[g * 128 + p];
.LBB0_251:
	s_ashr_i32 s12, s8, 3
	s_ashr_i32 s13, s12, 31
	s_lshl_b64 s[12:13], s[12:13], 7
	v_lshl_add_u64 v[196:197], s[12:13], 0, v[66:67]
	s_lshl_b32 s0, s10, 10
	v_lshlrev_b64 v[98:99], 13, v[196:197]
	v_lshl_add_u64 v[6:7], v[70:71], 0, s[0:1]
	v_lshl_add_u64 v[14:15], v[72:73], 0, s[0:1]
	v_lshl_add_u64 v[156:157], s[46:47], 0, v[98:99]
	s_lshl_b32 s0, s10, 9
	v_lshl_add_u64 v[156:157], v[156:157], 0, s[0:1]
	v_lshl_add_u64 v[156:157], v[156:157], 0, v[0:1]
	s_movk_i32 s10, 0x1000
	v_add_co_u32_e32 v156, vcc, s10, v156
	global_load_dwordx4 v[2:5], v[6:7], off offset:16
	global_load_dwordx4 v[10:13], v[6:7], off
	v_addc_co_u32_e32 v157, vcc, 0, v157, vcc
	global_load_dwordx4 v[6:9], v[14:15], off offset:16
	s_nop 0
	global_load_dwordx4 v[14:17], v[14:15], off
	v_lshl_add_u64 v[196:197], v[196:197], 3, s[50:51]
	global_load_dwordx4 v[156:159], v[156:157], off
	v_lshl_or_b32 v147, v114, 2, s0
	global_load_dwordx2 v[196:197], v[196:197], off
	s_add_i32 s8, s8, s3
	s_cmp_ge_i32 s8, s2
	v_lshl_add_u64 v[198:199], s[12:13], 0, v[84:85]
	v_lshlrev_b64 v[100:101], 13, v[198:199]
	v_lshl_add_u64 v[160:161], s[46:47], 0, v[100:101]
	v_lshl_add_u64 v[160:161], v[160:161], 0, s[0:1]
	v_lshl_add_u64 v[160:161], v[160:161], 0, v[0:1]
	v_add_co_u32_e32 v160, vcc, s10, v160
	v_lshl_add_u64 v[198:199], v[198:199], 3, s[50:51]
	s_nop 0
	v_addc_co_u32_e32 v161, vcc, 0, v161, vcc
	global_load_dwordx4 v[160:163], v[160:161], off
	s_nop 0
	global_load_dwordx2 v[198:199], v[198:199], off
	v_lshl_add_u64 v[200:201], s[12:13], 0, v[86:87]
	v_lshlrev_b64 v[102:103], 13, v[200:201]
	v_lshl_add_u64 v[164:165], s[46:47], 0, v[102:103]
	v_lshl_add_u64 v[164:165], v[164:165], 0, s[0:1]
	v_lshl_add_u64 v[164:165], v[164:165], 0, v[0:1]
	v_add_co_u32_e32 v164, vcc, s10, v164
	v_lshl_add_u64 v[200:201], v[200:201], 3, s[50:51]
	s_nop 0
	v_addc_co_u32_e32 v165, vcc, 0, v165, vcc
	global_load_dwordx4 v[164:167], v[164:165], off
	s_nop 0
	global_load_dwordx2 v[200:201], v[200:201], off
	v_lshl_add_u64 v[202:203], s[12:13], 0, v[88:89]
	v_lshlrev_b64 v[104:105], 13, v[202:203]
	v_lshl_add_u64 v[168:169], s[46:47], 0, v[104:105]
	v_lshl_add_u64 v[168:169], v[168:169], 0, s[0:1]
	v_lshl_add_u64 v[168:169], v[168:169], 0, v[0:1]
	v_add_co_u32_e32 v168, vcc, s10, v168
	v_lshl_add_u64 v[202:203], v[202:203], 3, s[50:51]
	s_nop 0
	v_addc_co_u32_e32 v169, vcc, 0, v169, vcc
	global_load_dwordx4 v[168:171], v[168:169], off
	s_nop 0
	global_load_dwordx2 v[202:203], v[202:203], off
	v_lshl_add_u64 v[208:209], s[12:13], 0, v[90:91]
	v_lshlrev_b64 v[106:107], 13, v[208:209]
	v_lshl_add_u64 v[172:173], s[46:47], 0, v[106:107]
	v_lshl_add_u64 v[172:173], v[172:173], 0, s[0:1]
	v_lshl_add_u64 v[172:173], v[172:173], 0, v[0:1]
	v_add_co_u32_e32 v172, vcc, s10, v172
	v_lshl_add_u64 v[208:209], v[208:209], 3, s[50:51]
	s_nop 0
	v_addc_co_u32_e32 v173, vcc, 0, v173, vcc
	global_load_dwordx4 v[172:175], v[172:173], off
	s_nop 0
	global_load_dwordx2 v[208:209], v[208:209], off
	v_lshl_add_u64 v[210:211], s[12:13], 0, v[92:93]
	v_lshlrev_b64 v[108:109], 13, v[210:211]
	v_lshl_add_u64 v[184:185], s[46:47], 0, v[108:109]
	v_lshl_add_u64 v[184:185], v[184:185], 0, s[0:1]
	v_lshl_add_u64 v[184:185], v[184:185], 0, v[0:1]
	v_add_co_u32_e32 v184, vcc, s10, v184
	v_lshl_add_u64 v[210:211], v[210:211], 3, s[50:51]
	s_nop 0
	v_addc_co_u32_e32 v185, vcc, 0, v185, vcc
	global_load_dwordx4 v[184:187], v[184:185], off
	s_nop 0
	global_load_dwordx2 v[210:211], v[210:211], off
	v_lshl_add_u64 v[212:213], s[12:13], 0, v[94:95]
	v_lshlrev_b64 v[110:111], 13, v[212:213]
	v_lshl_add_u64 v[188:189], s[46:47], 0, v[110:111]
	v_lshl_add_u64 v[188:189], v[188:189], 0, s[0:1]
	v_lshl_add_u64 v[188:189], v[188:189], 0, v[0:1]
	v_add_co_u32_e32 v188, vcc, s10, v188
	v_lshl_add_u64 v[212:213], v[212:213], 3, s[50:51]
	s_nop 0
	v_addc_co_u32_e32 v189, vcc, 0, v189, vcc
	global_load_dwordx4 v[188:191], v[188:189], off
	s_nop 0
	global_load_dwordx2 v[212:213], v[212:213], off
	v_lshl_add_u64 v[22:23], s[12:13], 0, v[96:97]
	v_lshlrev_b64 v[112:113], 13, v[22:23]
	v_lshl_add_u64 v[18:19], s[46:47], 0, v[112:113]
	v_lshl_add_u64 v[18:19], v[18:19], 0, s[0:1]
	v_lshl_add_u64 v[18:19], v[18:19], 0, v[0:1]
	v_add_co_u32_e32 v18, vcc, s10, v18
	v_lshl_add_u64 v[22:23], v[22:23], 3, s[50:51]
	s_nop 0
	v_addc_co_u32_e32 v19, vcc, 0, v19, vcc
	global_load_dwordx4 v[18:21], v[18:19], off
	s_nop 0
	global_load_dwordx2 v[22:23], v[22:23], off
	global_load_dword v224, v147, s[6:7]
	global_load_dword v225, v147, s[6:7] offset:128
	global_load_dword v226, v147, s[6:7] offset:256
	global_load_dword v227, v147, s[6:7] offset:384
	s_waitcnt vmcnt(18)
	v_lshlrev_b32_e32 v24, 16, v156
	v_and_b32_e32 v25, 0xffff0000, v156
	v_lshlrev_b32_e32 v156, 16, v157
	v_and_b32_e32 v157, 0xffff0000, v157
	v_lshlrev_b32_e32 v26, 16, v158
	v_and_b32_e32 v27, 0xffff0000, v158
	v_lshlrev_b32_e32 v28, 16, v159
	v_and_b32_e32 v29, 0xffff0000, v159
	v_sub_f32_e32 v157, v157, v196
	v_sub_f32_e32 v156, v156, v196
	v_sub_f32_e32 v159, v25, v196
	v_sub_f32_e32 v158, v24, v196
	v_pk_mul_f32 v[158:159], v[196:197], v[158:159] op_sel:[1,0]
	v_pk_mul_f32 v[156:157], v[196:197], v[156:157] op_sel:[1,0]
	v_sub_f32_e32 v27, v27, v196
	v_pk_fma_f32 v[24:25], v[12:13], v[156:157], v[16:17]
	v_pk_fma_f32 v[156:157], v[10:11], v[158:159], v[14:15]
	v_sub_f32_e32 v159, v29, v196
	v_sub_f32_e32 v158, v28, v196
	v_sub_f32_e32 v26, v26, v196
	v_pk_mul_f32 v[26:27], v[196:197], v[26:27] op_sel:[1,0]
	v_pk_mul_f32 v[158:159], v[196:197], v[158:159] op_sel:[1,0]
	v_cvt_pk_bf16_f32 v156, v156, v157
	v_pk_fma_f32 v[196:197], v[4:5], v[158:159], v[8:9]
	v_pk_fma_f32 v[158:159], v[2:3], v[26:27], v[6:7]
	v_cvt_pk_bf16_f32 v157, v24, v25
	v_cvt_pk_bf16_f32 v158, v158, v159
	v_cvt_pk_bf16_f32 v159, v196, v197
	ds_write_b128 v121, v[156:159]
	s_waitcnt vmcnt(16)
; #define LAS __attribute__((address_space(3)))
; __device__ __forceinline__ unsigned cvt_pk_bf16(float lo, float hi) { f32x2 v = {lo, hi}; bf16x2_t b = __builtin_convertvector(v, bf16x2_t); return __builtin_bit_cast(unsigned, b); }
; __device__ __forceinline__ float bf_lo(unsigned u) { return __uint_as_float(u << 16); }
; __device__ __forceinline__ float bf_hi(unsigned u) { return __uint_as_float(u & 0xffff0000u); }
; __device__ __forceinline__ void phase_spatial(const Args& a, LAS unsigned char* lds, int j, int nchunks) {
;     ...
;             for (int p = 0; p < 8; ++p) { const int row = lrow + 16 * p; const u32x4 w = *(const u32x4*)(Z + (row0 + row) * SGUW + SGUH + g * 256 + lch * 8);
;                 const f32x2 ms = *(const f32x2*)(st + 2 * (row0 + row));
;                 f32x4 x0 = {bf_lo(w.x), bf_hi(w.x), bf_lo(w.y), bf_hi(w.y)}, x1 = {bf_lo(w.z), bf_hi(w.z), bf_lo(w.w), bf_hi(w.w)};
;                 x0 = (x0 - ms.x) * ms.y * g0 + b0; x1 = (x1 - ms.x) * ms.y * g1 + b1;
;                 u32x4 o; o.x = cvt_pk_bf16(x0[0], x0[1]); o.y = cvt_pk_bf16(x0[2], x0[3]); o.z = cvt_pk_bf16(x1[0], x1[1]); o.w = cvt_pk_bf16(x1[2], x1[3]);
;                 *(LAS u32x4*)(vt + (lch >> 2) * 8192 + (row >> 3) * 512 + (row & 7) * 64 + (lch & 3) * 16) = o; }
	v_lshlrev_b32_e32 v24, 16, v160
	v_and_b32_e32 v25, 0xffff0000, v160
	v_lshlrev_b32_e32 v160, 16, v161
	v_and_b32_e32 v161, 0xffff0000, v161
	v_lshlrev_b32_e32 v26, 16, v162
	v_and_b32_e32 v27, 0xffff0000, v162
	v_lshlrev_b32_e32 v28, 16, v163
	v_and_b32_e32 v29, 0xffff0000, v163
	v_sub_f32_e32 v161, v161, v198
	v_sub_f32_e32 v160, v160, v198
	v_sub_f32_e32 v163, v25, v198
	v_sub_f32_e32 v162, v24, v198
	v_pk_mul_f32 v[162:163], v[198:199], v[162:163] op_sel:[1,0]
	v_pk_mul_f32 v[160:161], v[198:199], v[160:161] op_sel:[1,0]
	v_sub_f32_e32 v27, v27, v198
	v_pk_fma_f32 v[24:25], v[12:13], v[160:161], v[16:17]
	v_pk_fma_f32 v[160:161], v[10:11], v[162:163], v[14:15]
	v_sub_f32_e32 v163, v29, v198
	v_sub_f32_e32 v162, v28, v198
	v_sub_f32_e32 v26, v26, v198
	v_pk_mul_f32 v[26:27], v[198:199], v[26:27] op_sel:[1,0]
	v_pk_mul_f32 v[162:163], v[198:199], v[162:163] op_sel:[1,0]
	v_cvt_pk_bf16_f32 v160, v160, v161
	v_pk_fma_f32 v[198:199], v[4:5], v[162:163], v[8:9]
	v_pk_fma_f32 v[162:163], v[2:3], v[26:27], v[6:7]
	v_cvt_pk_bf16_f32 v161, v24, v25
	v_cvt_pk_bf16_f32 v162, v162, v163
	v_cvt_pk_bf16_f32 v163, v198, v199
	ds_write_b128 v122, v[160:163]
	s_waitcnt vmcnt(14)
	v_lshlrev_b32_e32 v24, 16, v164
	v_and_b32_e32 v25, 0xffff0000, v164
	v_lshlrev_b32_e32 v164, 16, v165
	v_and_b32_e32 v165, 0xffff0000, v165
	v_lshlrev_b32_e32 v26, 16, v166
	v_and_b32_e32 v27, 0xffff0000, v166
	v_lshlrev_b32_e32 v28, 16, v167
	v_and_b32_e32 v29, 0xffff0000, v167
	v_sub_f32_e32 v165, v165, v200
	v_sub_f32_e32 v164, v164, v200
	v_sub_f32_e32 v167, v25, v200
	v_sub_f32_e32 v166, v24, v200
	v_pk_mul_f32 v[166:167], v[200:201], v[166:167] op_sel:[1,0]
	v_pk_mul_f32 v[164:165], v[200:201], v[164:165] op_sel:[1,0]
	v_sub_f32_e32 v27, v27, v200
	v_pk_fma_f32 v[24:25], v[12:13], v[164:165], v[16:17]
	v_pk_fma_f32 v[164:165], v[10:11], v[166:167], v[14:15]
	v_sub_f32_e32 v167, v29, v200
	v_sub_f32_e32 v166, v28, v200
	v_sub_f32_e32 v26, v26, v200
	v_pk_mul_f32 v[26:27], v[200:201], v[26:27] op_sel:[1,0]
	v_pk_mul_f32 v[166:167], v[200:201], v[166:167] op_sel:[1,0]
	v_cvt_pk_bf16_f32 v164, v164, v165
	v_pk_fma_f32 v[200:201], v[4:5], v[166:167], v[8:9]
	v_pk_fma_f32 v[166:167], v[2:3], v[26:27], v[6:7]
	v_cvt_pk_bf16_f32 v165, v24, v25
	v_cvt_pk_bf16_f32 v166, v166, v167
	v_cvt_pk_bf16_f32 v167, v200, v201
	ds_write_b128 v123, v[164:167]
	s_waitcnt vmcnt(12)
	v_lshlrev_b32_e32 v24, 16, v168
	v_and_b32_e32 v25, 0xffff0000, v168
	v_lshlrev_b32_e32 v168, 16, v169
	v_and_b32_e32 v169, 0xffff0000, v169
	v_lshlrev_b32_e32 v26, 16, v170
	v_and_b32_e32 v27, 0xffff0000, v170
	v_lshlrev_b32_e32 v28, 16, v171
	v_and_b32_e32 v29, 0xffff0000, v171
	v_sub_f32_e32 v169, v169, v202
	v_sub_f32_e32 v168, v168, v202
	v_sub_f32_e32 v171, v25, v202
	v_sub_f32_e32 v170, v24, v202
	v_pk_mul_f32 v[170:171], v[202:203], v[170:171] op_sel:[1,0]
	v_pk_mul_f32 v[168:169], v[202:203], v[168:169] op_sel:[1,0]
	v_sub_f32_e32 v27, v27, v202
	v_pk_fma_f32 v[24:25], v[12:13], v[168:169], v[16:17]
	v_pk_fma_f32 v[168:169], v[10:11], v[170:171], v[14:15]
	v_sub_f32_e32 v171, v29, v202
	v_sub_f32_e32 v170, v28, v202
	v_sub_f32_e32 v26, v26, v202
	v_pk_mul_f32 v[26:27], v[202:203], v[26:27] op_sel:[1,0]
	v_pk_mul_f32 v[170:171], v[202:203], v[170:171] op_sel:[1,0]
	v_cvt_pk_bf16_f32 v168, v168, v169
	v_pk_fma_f32 v[202:203], v[4:5], v[170:171], v[8:9]
	v_pk_fma_f32 v[170:171], v[2:3], v[26:27], v[6:7]
	v_cvt_pk_bf16_f32 v169, v24, v25
	v_cvt_pk_bf16_f32 v170, v170, v171
	v_cvt_pk_bf16_f32 v171, v202, v203
	ds_write_b128 v124, v[168:171]
	s_waitcnt vmcnt(10)
	v_lshlrev_b32_e32 v24, 16, v172
	v_and_b32_e32 v25, 0xffff0000, v172
	v_lshlrev_b32_e32 v172, 16, v173
	v_and_b32_e32 v173, 0xffff0000, v173
	v_lshlrev_b32_e32 v26, 16, v174
	v_and_b32_e32 v27, 0xffff0000, v174
	v_lshlrev_b32_e32 v28, 16, v175
	v_and_b32_e32 v29, 0xffff0000, v175
	v_sub_f32_e32 v173, v173, v208
	v_sub_f32_e32 v172, v172, v208
	v_sub_f32_e32 v175, v25, v208
	v_sub_f32_e32 v174, v24, v208
	v_pk_mul_f32 v[174:175], v[208:209], v[174:175] op_sel:[1,0]
	v_pk_mul_f32 v[172:173], v[208:209], v[172:173] op_sel:[1,0]
	v_sub_f32_e32 v27, v27, v208
	v_pk_fma_f32 v[24:25], v[12:13], v[172:173], v[16:17]
	v_pk_fma_f32 v[172:173], v[10:11], v[174:175], v[14:15]
	v_sub_f32_e32 v175, v29, v208
	v_sub_f32_e32 v174, v28, v208
	v_sub_f32_e32 v26, v26, v208
	v_pk_mul_f32 v[26:27], v[208:209], v[26:27] op_sel:[1,0]
	v_pk_mul_f32 v[174:175], v[208:209], v[174:175] op_sel:[1,0]
	v_cvt_pk_bf16_f32 v172, v172, v173
	v_pk_fma_f32 v[208:209], v[4:5], v[174:175], v[8:9]
	v_pk_fma_f32 v[174:175], v[2:3], v[26:27], v[6:7]
	v_cvt_pk_bf16_f32 v173, v24, v25
	v_cvt_pk_bf16_f32 v174, v174, v175
	v_cvt_pk_bf16_f32 v175, v208, v209
	ds_write_b128 v125, v[172:175]
	s_waitcnt vmcnt(8)
	v_lshlrev_b32_e32 v24, 16, v184
	v_and_b32_e32 v25, 0xffff0000, v184
	v_lshlrev_b32_e32 v184, 16, v185
	v_and_b32_e32 v185, 0xffff0000, v185
	v_lshlrev_b32_e32 v26, 16, v186
	v_and_b32_e32 v27, 0xffff0000, v186
	v_lshlrev_b32_e32 v28, 16, v187
	v_and_b32_e32 v29, 0xffff0000, v187
	v_sub_f32_e32 v185, v185, v210
	v_sub_f32_e32 v184, v184, v210
	v_sub_f32_e32 v187, v25, v210
	v_sub_f32_e32 v186, v24, v210
	v_pk_mul_f32 v[186:187], v[210:211], v[186:187] op_sel:[1,0]
	v_pk_mul_f32 v[184:185], v[210:211], v[184:185] op_sel:[1,0]
	v_sub_f32_e32 v27, v27, v210
	v_pk_fma_f32 v[24:25], v[12:13], v[184:185], v[16:17]
	v_pk_fma_f32 v[184:185], v[10:11], v[186:187], v[14:15]
	v_sub_f32_e32 v187, v29, v210
	v_sub_f32_e32 v186, v28, v210
	v_sub_f32_e32 v26, v26, v210
	v_pk_mul_f32 v[26:27], v[210:211], v[26:27] op_sel:[1,0]
	v_pk_mul_f32 v[186:187], v[210:211], v[186:187] op_sel:[1,0]
	v_cvt_pk_bf16_f32 v184, v184, v185
	v_pk_fma_f32 v[210:211], v[4:5], v[186:187], v[8:9]
	v_pk_fma_f32 v[186:187], v[2:3], v[26:27], v[6:7]
	v_cvt_pk_bf16_f32 v185, v24, v25
	v_cvt_pk_bf16_f32 v186, v186, v187
	v_cvt_pk_bf16_f32 v187, v210, v211
	ds_write_b128 v126, v[184:187]
	s_waitcnt vmcnt(6)
; #define LAS __attribute__((address_space(3)))
; __device__ __forceinline__ unsigned cvt_pk_bf16(float lo, float hi) { f32x2 v = {lo, hi}; bf16x2_t b = __builtin_convertvector(v, bf16x2_t); return __builtin_bit_cast(unsigned, b); }
; __device__ __forceinline__ float bf_lo(unsigned u) { return __uint_as_float(u << 16); }
; __device__ __forceinline__ float bf_hi(unsigned u) { return __uint_as_float(u & 0xffff0000u); }
; __device__ __forceinline__ void phase_spatial(const Args& a, LAS unsigned char* lds, int j, int nchunks) {
;     ...
;             for (int p = 0; p < 8; ++p) { const int row = lrow + 16 * p; const u32x4 w = *(const u32x4*)(Z + (row0 + row) * SGUW + SGUH + g * 256 + lch * 8);
;                 const f32x2 ms = *(const f32x2*)(st + 2 * (row0 + row));
;                 f32x4 x0 = {bf_lo(w.x), bf_hi(w.x), bf_lo(w.y), bf_hi(w.y)}, x1 = {bf_lo(w.z), bf_hi(w.z), bf_lo(w.w), bf_hi(w.w)};
;                 x0 = (x0 - ms.x) * ms.y * g0 + b0; x1 = (x1 - ms.x) * ms.y * g1 + b1;
;                 u32x4 o; o.x = cvt_pk_bf16(x0[0], x0[1]); o.y = cvt_pk_bf16(x0[2], x0[3]); o.z = cvt_pk_bf16(x1[0], x1[1]); o.w = cvt_pk_bf16(x1[2], x1[3]);
;                 *(LAS u32x4*)(vt + (lch >> 2) * 8192 + (row >> 3) * 512 + (row & 7) * 64 + (lch & 3) * 16) = o; }
;         }
;         __syncthreads();
;         f32x16 acc[4];
; #pragma unroll
;         for (int pb = 0; pb < 4; ++pb)
; #pragma unroll
;             for (int i = 0; i < 16; ++i) acc[pb][i] = 0.f;
;         const int vb = wid * 8192 + ((lane >> 4) & 1) * 32 + (lane & 3) * 8 + ((lane & 15) >> 2) * 64;
; #pragma unroll
;         for (int ks = 0; ks < 8; ++ks) {
;             const s16x4 lo = __builtin_bit_cast(s16x4, __builtin_amdgcn_ds_read_tr16_b64_v4i16((LAS s16x4*)(vt + vb + (2 * ks + hi) * 512)));
;             const s16x4 hh = __builtin_bit_cast(s16x4, __builtin_amdgcn_ds_read_tr16_b64_v4i16((LAS s16x4*)(vt + vb + (2 * ks + hi) * 512 + 256)));
;             const bf16x8 vf = __builtin_shufflevector(lo, hh, 0, 1, 2, 3, 4, 5, 6, 7);
; #pragma unroll
;             for (int pb = 0; pb < 4; ++pb) { const int row = 32 * pb + r32; const bf16x8 wf = *(const LAS bf16x8*)(wl + row * 256 + (((2 * ks + hi) ^ (row & 15)) << 4));
;                 acc[pb] = __builtin_amdgcn_mfma_f32_32x32x16_bf16(vf, wf, acc[pb], 0, 0, 0); }
;         }
	v_lshlrev_b32_e32 v24, 16, v188
	v_and_b32_e32 v25, 0xffff0000, v188
	v_lshlrev_b32_e32 v188, 16, v189
	v_and_b32_e32 v189, 0xffff0000, v189
	v_lshlrev_b32_e32 v26, 16, v190
	v_and_b32_e32 v27, 0xffff0000, v190
	v_lshlrev_b32_e32 v28, 16, v191
	v_and_b32_e32 v29, 0xffff0000, v191
	v_sub_f32_e32 v189, v189, v212
	v_sub_f32_e32 v188, v188, v212
	v_sub_f32_e32 v191, v25, v212
	v_sub_f32_e32 v190, v24, v212
	v_pk_mul_f32 v[190:191], v[212:213], v[190:191] op_sel:[1,0]
	v_pk_mul_f32 v[188:189], v[212:213], v[188:189] op_sel:[1,0]
	v_sub_f32_e32 v27, v27, v212
	v_pk_fma_f32 v[24:25], v[12:13], v[188:189], v[16:17]
	v_pk_fma_f32 v[188:189], v[10:11], v[190:191], v[14:15]
	v_sub_f32_e32 v191, v29, v212
	v_sub_f32_e32 v190, v28, v212
	v_sub_f32_e32 v26, v26, v212
	v_pk_mul_f32 v[26:27], v[212:213], v[26:27] op_sel:[1,0]
	v_pk_mul_f32 v[190:191], v[212:213], v[190:191] op_sel:[1,0]
	v_cvt_pk_bf16_f32 v188, v188, v189
	v_pk_fma_f32 v[212:213], v[4:5], v[190:191], v[8:9]
	v_pk_fma_f32 v[190:191], v[2:3], v[26:27], v[6:7]
	v_cvt_pk_bf16_f32 v189, v24, v25
	v_cvt_pk_bf16_f32 v190, v190, v191
	v_cvt_pk_bf16_f32 v191, v212, v213
	ds_write_b128 v127, v[188:191]
	s_waitcnt vmcnt(4)
	v_lshlrev_b32_e32 v24, 16, v18
	v_and_b32_e32 v25, 0xffff0000, v18
	v_lshlrev_b32_e32 v18, 16, v19
	v_and_b32_e32 v19, 0xffff0000, v19
	v_lshlrev_b32_e32 v26, 16, v20
	v_and_b32_e32 v27, 0xffff0000, v20
	v_lshlrev_b32_e32 v28, 16, v21
	v_and_b32_e32 v29, 0xffff0000, v21
	v_sub_f32_e32 v19, v19, v22
	v_sub_f32_e32 v18, v18, v22
	v_sub_f32_e32 v21, v25, v22
	v_sub_f32_e32 v20, v24, v22
	v_pk_mul_f32 v[20:21], v[22:23], v[20:21] op_sel:[1,0]
	v_pk_mul_f32 v[18:19], v[22:23], v[18:19] op_sel:[1,0]
	v_pk_fma_f32 v[10:11], v[10:11], v[20:21], v[14:15]
	v_pk_fma_f32 v[12:13], v[12:13], v[18:19], v[16:17]
	v_sub_f32_e32 v15, v29, v22
	v_sub_f32_e32 v14, v28, v22
	v_sub_f32_e32 v17, v27, v22
	v_sub_f32_e32 v16, v26, v22
	v_pk_mul_f32 v[16:17], v[22:23], v[16:17] op_sel:[1,0]
	v_pk_mul_f32 v[14:15], v[22:23], v[14:15] op_sel:[1,0]
	s_nop 0
	v_pk_fma_f32 v[8:9], v[4:5], v[14:15], v[8:9]
	v_pk_fma_f32 v[4:5], v[2:3], v[16:17], v[6:7]
	v_cvt_pk_bf16_f32 v2, v10, v11
	v_cvt_pk_bf16_f32 v3, v12, v13
	v_cvt_pk_bf16_f32 v4, v4, v5
	v_cvt_pk_bf16_f32 v5, v8, v9
	ds_write_b128 v128, v[2:5]
	s_waitcnt lgkmcnt(0)
	s_barrier
	ds_read_b64_tr_b16 v[156:157], v129
	ds_read_b64_tr_b16 v[158:159], v129 offset:256
	ds_read_b128 v[164:167], v130
	ds_read_b128 v[168:171], v130 offset:8192
	ds_read_b128 v[172:175], v130 offset:16384
	ds_read_b128 v[184:187], v130 offset:24576
	ds_read_b64_tr_b16 v[160:161], v131
	ds_read_b64_tr_b16 v[162:163], v131 offset:256
	ds_read_b128 v[188:191], v132
	ds_read_b128 v[192:195], v132 offset:8192
	ds_read_b128 v[196:199], v132 offset:16384
	ds_read_b128 v[200:203], v132 offset:24576
	s_waitcnt lgkmcnt(9)
	v_mfma_f32_32x32x16_bf16 v[50:65], v[156:159], v[164:167], 0
	s_waitcnt lgkmcnt(8)
	v_mfma_f32_32x32x16_bf16 v[34:49], v[156:159], v[168:171], 0
	s_waitcnt lgkmcnt(7)
	v_mfma_f32_32x32x16_bf16 v[18:33], v[156:159], v[172:175], 0
	s_waitcnt lgkmcnt(6)
	v_mfma_f32_32x32x16_bf16 v[2:17], v[156:159], v[184:187], 0
	ds_read_b64_tr_b16 v[156:157], v133
	ds_read_b64_tr_b16 v[158:159], v133 offset:256
	ds_read_b128 v[164:167], v134
	ds_read_b128 v[168:171], v134 offset:8192
	ds_read_b128 v[172:175], v134 offset:16384
	ds_read_b128 v[184:187], v134 offset:24576
	s_waitcnt lgkmcnt(9)
	v_mfma_f32_32x32x16_bf16 v[50:65], v[160:163], v[188:191], v[50:65]
	s_waitcnt lgkmcnt(8)
	v_mfma_f32_32x32x16_bf16 v[34:49], v[160:163], v[192:195], v[34:49]
	s_waitcnt lgkmcnt(7)
	v_mfma_f32_32x32x16_bf16 v[18:33], v[160:163], v[196:199], v[18:33]
	s_waitcnt lgkmcnt(6)
	v_mfma_f32_32x32x16_bf16 v[2:17], v[160:163], v[200:203], v[2:17]
	ds_read_b64_tr_b16 v[160:161], v135
	ds_read_b64_tr_b16 v[162:163], v135 offset:256
	ds_read_b128 v[188:191], v136
	ds_read_b128 v[192:195], v136 offset:8192
	ds_read_b128 v[196:199], v136 offset:16384
	ds_read_b128 v[200:203], v136 offset:24576
	s_waitcnt lgkmcnt(9)
	v_mfma_f32_32x32x16_bf16 v[50:65], v[156:159], v[164:167], v[50:65]
	s_waitcnt lgkmcnt(8)
	v_mfma_f32_32x32x16_bf16 v[34:49], v[156:159], v[168:171], v[34:49]
	s_waitcnt lgkmcnt(7)
	v_mfma_f32_32x32x16_bf16 v[18:33], v[156:159], v[172:175], v[18:33]
	s_waitcnt lgkmcnt(6)
	v_mfma_f32_32x32x16_bf16 v[2:17], v[156:159], v[184:187], v[2:17]
	ds_read_b64_tr_b16 v[156:157], v137
	ds_read_b64_tr_b16 v[158:159], v137 offset:256
	ds_read_b128 v[164:167], v138
	ds_read_b128 v[168:171], v138 offset:8192
	ds_read_b128 v[172:175], v138 offset:16384
	ds_read_b128 v[184:187], v138 offset:24576
	s_waitcnt lgkmcnt(9)
	v_mfma_f32_32x32x16_bf16 v[50:65], v[160:163], v[188:191], v[50:65]
	s_waitcnt lgkmcnt(8)
	v_mfma_f32_32x32x16_bf16 v[34:49], v[160:163], v[192:195], v[34:49]
	s_waitcnt lgkmcnt(7)
	v_mfma_f32_32x32x16_bf16 v[18:33], v[160:163], v[196:199], v[18:33]
	s_waitcnt lgkmcnt(6)
	v_mfma_f32_32x32x16_bf16 v[2:17], v[160:163], v[200:203], v[2:17]
	ds_read_b64_tr_b16 v[160:161], v139
	ds_read_b64_tr_b16 v[162:163], v139 offset:256
	ds_read_b128 v[188:191], v140
	ds_read_b128 v[192:195], v140 offset:8192
	ds_read_b128 v[196:199], v140 offset:16384
	ds_read_b128 v[200:203], v140 offset:24576
	s_waitcnt lgkmcnt(9)
	v_mfma_f32_32x32x16_bf16 v[50:65], v[156:159], v[164:167], v[50:65]
	s_waitcnt lgkmcnt(8)
	v_mfma_f32_32x32x16_bf16 v[34:49], v[156:159], v[168:171], v[34:49]
	s_waitcnt lgkmcnt(7)
	v_mfma_f32_32x32x16_bf16 v[18:33], v[156:159], v[172:175], v[18:33]
	s_waitcnt lgkmcnt(6)
; #define LAS __attribute__((address_space(3)))
; __device__ __forceinline__ unsigned cvt_pk_bf16(float lo, float hi) { f32x2 v = {lo, hi}; bf16x2_t b = __builtin_convertvector(v, bf16x2_t); return __builtin_bit_cast(unsigned, b); }
; __device__ __forceinline__ void phase_spatial(const Args& a, LAS unsigned char* lds, int j, int nchunks) {
;     ...
;         for (int ks = 0; ks < 8; ++ks) {
;             const s16x4 lo = __builtin_bit_cast(s16x4, __builtin_amdgcn_ds_read_tr16_b64_v4i16((LAS s16x4*)(vt + vb + (2 * ks + hi) * 512)));
;             const s16x4 hh = __builtin_bit_cast(s16x4, __builtin_amdgcn_ds_read_tr16_b64_v4i16((LAS s16x4*)(vt + vb + (2 * ks + hi) * 512 + 256)));
;             const bf16x8 vf = __builtin_shufflevector(lo, hh, 0, 1, 2, 3, 4, 5, 6, 7);
; #pragma unroll
;             for (int pb = 0; pb < 4; ++pb) { const int row = 32 * pb + r32; const bf16x8 wf = *(const LAS bf16x8*)(wl + row * 256 + (((2 * ks + hi) ^ (row & 15)) << 4));
;                 acc[pb] = __builtin_amdgcn_mfma_f32_32x32x16_bf16(vf, wf, acc[pb], 0, 0, 0); }
;         }
;         __syncthreads();
; #pragma unroll
;         for (int pb = 0; pb < 4; ++pb) { const int p = 32 * pb + r32; const float bias = bs[g * 128 + p];
; #pragma unroll
;             for (int g4 = 0; g4 < 4; ++g4) { u32x2 w; w.x = cvt_pk_bf16(acc[pb][4 * g4] + bias, acc[pb][4 * g4 + 1] + bias); w.y = cvt_pk_bf16(acc[pb][4 * g4 + 2] + bias, acc[pb][4 * g4 + 3] + bias);
;                 *(LAS u32x2*)(vt + p * 520 + (32 * wid + 8 * g4 + 4 * hi) * 2) = w; } }
	v_mfma_f32_32x32x16_bf16 v[2:17], v[156:159], v[184:187], v[2:17]
	ds_read_b64_tr_b16 v[156:157], v141
	ds_read_b64_tr_b16 v[158:159], v141 offset:256
	ds_read_b128 v[164:167], v142
	ds_read_b128 v[168:171], v142 offset:8192
	ds_read_b128 v[172:175], v142 offset:16384
	ds_read_b128 v[184:187], v142 offset:24576
	s_waitcnt lgkmcnt(9)
	v_mfma_f32_32x32x16_bf16 v[50:65], v[160:163], v[188:191], v[50:65]
	s_waitcnt lgkmcnt(8)
	v_mfma_f32_32x32x16_bf16 v[34:49], v[160:163], v[192:195], v[34:49]
	s_waitcnt lgkmcnt(7)
	v_mfma_f32_32x32x16_bf16 v[18:33], v[160:163], v[196:199], v[18:33]
	s_waitcnt lgkmcnt(6)
	v_mfma_f32_32x32x16_bf16 v[2:17], v[160:163], v[200:203], v[2:17]
	ds_read_b64_tr_b16 v[160:161], v143
	ds_read_b64_tr_b16 v[162:163], v143 offset:256
	ds_read_b128 v[188:191], v144
	ds_read_b128 v[192:195], v144 offset:8192
	ds_read_b128 v[196:199], v144 offset:16384
	ds_read_b128 v[200:203], v144 offset:24576
	s_waitcnt lgkmcnt(9)
	v_mfma_f32_32x32x16_bf16 v[50:65], v[156:159], v[164:167], v[50:65]
	s_waitcnt lgkmcnt(8)
	v_mfma_f32_32x32x16_bf16 v[34:49], v[156:159], v[168:171], v[34:49]
	s_waitcnt lgkmcnt(7)
	v_mfma_f32_32x32x16_bf16 v[18:33], v[156:159], v[172:175], v[18:33]
	s_waitcnt lgkmcnt(6)
	v_mfma_f32_32x32x16_bf16 v[2:17], v[156:159], v[184:187], v[2:17]
	s_waitcnt lgkmcnt(3)
	v_mfma_f32_32x32x16_bf16 v[50:65], v[160:163], v[188:191], v[50:65]
	s_waitcnt lgkmcnt(2)
	v_mfma_f32_32x32x16_bf16 v[34:49], v[160:163], v[192:195], v[34:49]
	s_waitcnt lgkmcnt(1)
	v_mfma_f32_32x32x16_bf16 v[18:33], v[160:163], v[196:199], v[18:33]
	s_waitcnt lgkmcnt(0)
	s_barrier
	v_mfma_f32_32x32x16_bf16 v[2:17], v[160:163], v[200:203], v[2:17]
	s_nop 4
	s_waitcnt vmcnt(0)
	v_mov_b32_e32 v148, v224
	s_waitcnt vmcnt(0)
	v_add_f32_e64 v50, v50, v148
	v_add_f32_e64 v51, v51, v148
	v_add_f32_e64 v52, v52, v148
	v_add_f32_e64 v53, v53, v148
	v_cvt_pk_bf16_f32 v50, v50, v51
	v_cvt_pk_bf16_f32 v51, v52, v53
	v_pk_add_f32 v[52:53], v[54:55], v[148:149] op_sel_hi:[1,0]
	v_pk_add_f32 v[54:55], v[56:57], v[148:149] op_sel_hi:[1,0]
	v_cvt_pk_bf16_f32 v52, v52, v53
	v_cvt_pk_bf16_f32 v53, v54, v55
	ds_write2_b64 v145, v[50:51], v[52:53] offset1:2
	v_pk_add_f32 v[50:51], v[58:59], v[148:149] op_sel_hi:[1,0]
	v_pk_add_f32 v[52:53], v[60:61], v[148:149] op_sel_hi:[1,0]
	v_cvt_pk_bf16_f32 v50, v50, v51
	v_cvt_pk_bf16_f32 v51, v52, v53
	v_pk_add_f32 v[52:53], v[62:63], v[148:149] op_sel_hi:[1,0]
	v_pk_add_f32 v[54:55], v[64:65], v[148:149] op_sel_hi:[1,0]
	v_cvt_pk_bf16_f32 v52, v52, v53
	v_cvt_pk_bf16_f32 v53, v54, v55
	ds_write2_b64 v145, v[50:51], v[52:53] offset0:4 offset1:6
	s_waitcnt vmcnt(0)
	v_mov_b32_e32 v50, v225
	s_waitcnt vmcnt(0)
	v_pk_add_f32 v[34:35], v[34:35], v[50:51] op_sel_hi:[1,0]
	v_pk_add_f32 v[36:37], v[36:37], v[50:51] op_sel_hi:[1,0]
	v_cvt_pk_bf16_f32 v34, v34, v35
	v_cvt_pk_bf16_f32 v35, v36, v37
	v_pk_add_f32 v[36:37], v[38:39], v[50:51] op_sel_hi:[1,0]
	v_pk_add_f32 v[38:39], v[40:41], v[50:51] op_sel_hi:[1,0]
	v_cvt_pk_bf16_f32 v36, v36, v37
	v_cvt_pk_bf16_f32 v37, v38, v39
	v_add_u32_e32 v40, 0x4000, v145
	ds_write2_b64 v40, v[34:35], v[36:37] offset0:32 offset1:34
	v_pk_add_f32 v[34:35], v[42:43], v[50:51] op_sel_hi:[1,0]
	v_pk_add_f32 v[36:37], v[44:45], v[50:51] op_sel_hi:[1,0]
	v_cvt_pk_bf16_f32 v34, v34, v35
	v_cvt_pk_bf16_f32 v35, v36, v37
	v_pk_add_f32 v[36:37], v[46:47], v[50:51] op_sel_hi:[1,0]
	v_pk_add_f32 v[38:39], v[48:49], v[50:51] op_sel_hi:[1,0]
	v_cvt_pk_bf16_f32 v36, v36, v37
	v_cvt_pk_bf16_f32 v37, v38, v39
	ds_write2_b64 v40, v[34:35], v[36:37] offset0:36 offset1:38
	s_waitcnt vmcnt(0)
	v_mov_b32_e32 v34, v226
	v_add_u32_e32 v48, v115, v116
	s_waitcnt vmcnt(0)
	v_pk_add_f32 v[18:19], v[18:19], v[34:35] op_sel_hi:[1,0]
	v_pk_add_f32 v[20:21], v[20:21], v[34:35] op_sel_hi:[1,0]
	v_cvt_pk_bf16_f32 v18, v18, v19
	v_cvt_pk_bf16_f32 v19, v20, v21
	v_pk_add_f32 v[20:21], v[22:23], v[34:35] op_sel_hi:[1,0]
	v_pk_add_f32 v[22:23], v[24:25], v[34:35] op_sel_hi:[1,0]
	v_cvt_pk_bf16_f32 v20, v20, v21
	v_cvt_pk_bf16_f32 v21, v22, v23
	v_add_u32_e32 v24, 0x8000, v145
	ds_write2_b64 v24, v[18:19], v[20:21] offset0:64 offset1:66
	v_pk_add_f32 v[18:19], v[26:27], v[34:35] op_sel_hi:[1,0]
	v_pk_add_f32 v[20:21], v[28:29], v[34:35] op_sel_hi:[1,0]
	v_cvt_pk_bf16_f32 v18, v18, v19
	v_cvt_pk_bf16_f32 v19, v20, v21
	v_pk_add_f32 v[20:21], v[30:31], v[34:35] op_sel_hi:[1,0]
	v_pk_add_f32 v[22:23], v[32:33], v[34:35] op_sel_hi:[1,0]
	v_cvt_pk_bf16_f32 v20, v20, v21
	v_cvt_pk_bf16_f32 v21, v22, v23
	ds_write2_b64 v24, v[18:19], v[20:21] offset0:68 offset1:70
	s_waitcnt vmcnt(0)
	v_mov_b32_e32 v18, v227
	s_waitcnt vmcnt(0)
	v_pk_add_f32 v[2:3], v[2:3], v[18:19] op_sel_hi:[1,0]
	v_pk_add_f32 v[4:5], v[4:5], v[18:19] op_sel_hi:[1,0]
	v_cvt_pk_bf16_f32 v2, v2, v3
	v_cvt_pk_bf16_f32 v3, v4, v5
	v_pk_add_f32 v[4:5], v[6:7], v[18:19] op_sel_hi:[1,0]
	v_pk_add_f32 v[6:7], v[8:9], v[18:19] op_sel_hi:[1,0]
	v_cvt_pk_bf16_f32 v4, v4, v5
	v_cvt_pk_bf16_f32 v5, v6, v7
	v_add_u32_e32 v8, 0xc000, v145
	ds_write2_b64 v8, v[2:3], v[4:5] offset0:96 offset1:98
	v_pk_add_f32 v[2:3], v[10:11], v[18:19] op_sel_hi:[1,0]
	v_pk_add_f32 v[4:5], v[12:13], v[18:19] op_sel_hi:[1,0]
	v_cvt_pk_bf16_f32 v2, v2, v3
	v_cvt_pk_bf16_f32 v3, v4, v5
	v_pk_add_f32 v[4:5], v[14:15], v[18:19] op_sel_hi:[1,0]
	v_pk_add_f32 v[6:7], v[16:17], v[18:19] op_sel_hi:[1,0]
	v_cvt_pk_bf16_f32 v4, v4, v5
	v_cvt_pk_bf16_f32 v5, v6, v7
	ds_write2_b64 v8, v[2:3], v[4:5] offset0:100 offset1:102
	v_lshl_add_u64 v[2:3], v[74:75], 0, s[0:1]
	v_lshl_add_u64 v[52:53], v[2:3], 0, v[98:99]
	s_waitcnt lgkmcnt(0)
	s_barrier
; #define LAS __attribute__((address_space(3)))
; __device__ __forceinline__ unsigned cvt_pk_bf16(float lo, float hi) { f32x2 v = {lo, hi}; bf16x2_t b = __builtin_convertvector(v, bf16x2_t); return __builtin_bit_cast(unsigned, b); }
; __device__ __forceinline__ float bf_lo(unsigned u) { return __uint_as_float(u << 16); }
; __device__ __forceinline__ float bf_hi(unsigned u) { return __uint_as_float(u & 0xffff0000u); }
; __device__ __forceinline__ void phase_spatial(const Args& a, LAS unsigned char* lds, int j, int nchunks) {
;     ...
;         { u32x4 uu[8];
; #pragma unroll
;           for (int p8 = 0; p8 < 8; ++p8) { const int row = lrow + 16 * p8; uu[p8] = *(const u32x4*)(Z + (row0 + row) * SGUW + g * 256 + lch * 8); }
; #pragma unroll
;           for (int p8 = 0; p8 < 8; ++p8) { const int row = lrow + 16 * p8; const u32x2 s0 = *(const LAS u32x2*)(vt + row * 520 + lch * 16), s1 = *(const LAS u32x2*)(vt + row * 520 + lch * 16 + 8);
;               u32x4 o; o.x = cvt_pk_bf16(bf_lo(uu[p8].x) * bf_lo(s0.x), bf_hi(uu[p8].x) * bf_hi(s0.x)); o.y = cvt_pk_bf16(bf_lo(uu[p8].y) * bf_lo(s0.y), bf_hi(uu[p8].y) * bf_hi(s0.y));
;               o.z = cvt_pk_bf16(bf_lo(uu[p8].z) * bf_lo(s1.x), bf_hi(uu[p8].z) * bf_hi(s1.x)); o.w = cvt_pk_bf16(bf_lo(uu[p8].w) * bf_lo(s1.y), bf_hi(uu[p8].w) * bf_hi(s1.y));
;               *(u32x4*)(Z + (row0 + row) * SGUW + g * 256 + lch * 8) = o; } }
	global_load_dwordx4 v[44:47], v[52:53], off
	v_lshl_add_u64 v[42:43], v[2:3], 0, v[100:101]
	global_load_dwordx4 v[26:29], v[42:43], off
	v_lshl_add_u64 v[40:41], v[2:3], 0, v[102:103]
	global_load_dwordx4 v[22:25], v[40:41], off
	v_lshl_add_u64 v[38:39], v[2:3], 0, v[104:105]
	global_load_dwordx4 v[18:21], v[38:39], off
	v_lshl_add_u64 v[36:37], v[2:3], 0, v[106:107]
	global_load_dwordx4 v[14:17], v[36:37], off
	v_lshl_add_u64 v[34:35], v[2:3], 0, v[108:109]
	global_load_dwordx4 v[10:13], v[34:35], off
	ds_read2_b64 v[48:51], v48 offset1:1
	v_lshl_add_u64 v[32:33], v[2:3], 0, v[110:111]
	global_load_dwordx4 v[6:9], v[32:33], off
	v_lshl_add_u64 v[30:31], v[2:3], 0, v[112:113]
	global_load_dwordx4 v[2:5], v[30:31], off
	s_waitcnt lgkmcnt(0)
	v_lshlrev_b32_e32 v56, 16, v48
	v_and_b32_e32 v57, 0xffff0000, v48
	v_lshlrev_b32_e32 v48, 16, v49
	v_and_b32_e32 v49, 0xffff0000, v49
	s_waitcnt vmcnt(7)
	v_lshlrev_b32_e32 v54, 16, v44
	v_and_b32_e32 v55, 0xffff0000, v44
	v_pk_mul_f32 v[54:55], v[54:55], v[56:57]
	s_nop 0
	v_cvt_pk_bf16_f32 v44, v54, v55
	v_lshlrev_b32_e32 v54, 16, v45
	v_and_b32_e32 v55, 0xffff0000, v45
	v_pk_mul_f32 v[48:49], v[54:55], v[48:49]
	v_lshlrev_b32_e32 v54, 16, v50
	v_cvt_pk_bf16_f32 v45, v48, v49
	v_lshlrev_b32_e32 v48, 16, v46
	v_and_b32_e32 v49, 0xffff0000, v46
	v_and_b32_e32 v55, 0xffff0000, v50
	v_pk_mul_f32 v[48:49], v[48:49], v[54:55]
	v_lshlrev_b32_e32 v50, 16, v51
	v_cvt_pk_bf16_f32 v46, v48, v49
	v_lshlrev_b32_e32 v48, 16, v47
	v_and_b32_e32 v49, 0xffff0000, v47
	v_and_b32_e32 v51, 0xffff0000, v51
	v_pk_mul_f32 v[48:49], v[48:49], v[50:51]
	s_nop 0
	v_cvt_pk_bf16_f32 v47, v48, v49
	global_store_dwordx4 v[52:53], v[44:47], off
	ds_read2_b64 v[44:47], v146 offset1:1
	s_waitcnt vmcnt(7)
	v_lshlrev_b32_e32 v48, 16, v26
	v_and_b32_e32 v49, 0xffff0000, v26
	s_waitcnt lgkmcnt(0)
	v_lshlrev_b32_e32 v50, 16, v44
	v_and_b32_e32 v51, 0xffff0000, v44
	v_pk_mul_f32 v[48:49], v[48:49], v[50:51]
	v_lshlrev_b32_e32 v44, 16, v45
	v_cvt_pk_bf16_f32 v26, v48, v49
	v_lshlrev_b32_e32 v48, 16, v27
	v_and_b32_e32 v49, 0xffff0000, v27
	v_and_b32_e32 v45, 0xffff0000, v45
	v_pk_mul_f32 v[44:45], v[48:49], v[44:45]
	v_lshlrev_b32_e32 v48, 16, v46
	v_cvt_pk_bf16_f32 v27, v44, v45
	v_lshlrev_b32_e32 v44, 16, v28
	v_and_b32_e32 v45, 0xffff0000, v28
	v_and_b32_e32 v49, 0xffff0000, v46
	v_pk_mul_f32 v[44:45], v[44:45], v[48:49]
	v_lshlrev_b32_e32 v46, 16, v47
	v_cvt_pk_bf16_f32 v28, v44, v45
	v_lshlrev_b32_e32 v44, 16, v29
	v_and_b32_e32 v45, 0xffff0000, v29
	v_and_b32_e32 v47, 0xffff0000, v47
	v_pk_mul_f32 v[44:45], v[44:45], v[46:47]
	s_nop 0
	v_cvt_pk_bf16_f32 v29, v44, v45
	global_store_dwordx4 v[42:43], v[26:29], off
	s_waitcnt vmcnt(7)
	v_lshlrev_b32_e32 v42, 16, v22
	v_and_b32_e32 v43, 0xffff0000, v22
	v_add_u32_e32 v26, 0x2080, v146
	ds_read2_b64 v[26:29], v26 offset1:1
	s_waitcnt lgkmcnt(0)
	v_lshlrev_b32_e32 v44, 16, v26
	v_and_b32_e32 v45, 0xffff0000, v26
	v_pk_mul_f32 v[42:43], v[42:43], v[44:45]
	v_lshlrev_b32_e32 v26, 16, v27
	v_cvt_pk_bf16_f32 v22, v42, v43
	v_lshlrev_b32_e32 v42, 16, v23
	v_and_b32_e32 v43, 0xffff0000, v23
	v_and_b32_e32 v27, 0xffff0000, v27
	v_pk_mul_f32 v[26:27], v[42:43], v[26:27]
	v_lshlrev_b32_e32 v42, 16, v28
	v_cvt_pk_bf16_f32 v23, v26, v27
	v_lshlrev_b32_e32 v26, 16, v24
	v_and_b32_e32 v27, 0xffff0000, v24
	v_and_b32_e32 v43, 0xffff0000, v28
	v_pk_mul_f32 v[26:27], v[26:27], v[42:43]
	v_lshlrev_b32_e32 v28, 16, v29
	v_cvt_pk_bf16_f32 v24, v26, v27
	v_lshlrev_b32_e32 v26, 16, v25
	v_and_b32_e32 v27, 0xffff0000, v25
	v_and_b32_e32 v29, 0xffff0000, v29
	v_pk_mul_f32 v[26:27], v[26:27], v[28:29]
	s_nop 0
	v_cvt_pk_bf16_f32 v25, v26, v27
	global_store_dwordx4 v[40:41], v[22:25], off
	s_waitcnt vmcnt(7)
	v_lshlrev_b32_e32 v26, 16, v18
	v_and_b32_e32 v27, 0xffff0000, v18
	v_add_u32_e32 v22, 0x4100, v146
	ds_read2_b64 v[22:25], v22 offset1:1
	s_waitcnt lgkmcnt(0)
	v_lshlrev_b32_e32 v28, 16, v22
	v_and_b32_e32 v29, 0xffff0000, v22
	v_pk_mul_f32 v[26:27], v[26:27], v[28:29]
	v_lshlrev_b32_e32 v22, 16, v23
	v_cvt_pk_bf16_f32 v18, v26, v27
	v_lshlrev_b32_e32 v26, 16, v19
	v_and_b32_e32 v27, 0xffff0000, v19
	v_and_b32_e32 v23, 0xffff0000, v23
	v_pk_mul_f32 v[22:23], v[26:27], v[22:23]
	v_lshlrev_b32_e32 v26, 16, v24
	v_cvt_pk_bf16_f32 v19, v22, v23
	v_lshlrev_b32_e32 v22, 16, v20
	v_and_b32_e32 v23, 0xffff0000, v20
	v_and_b32_e32 v27, 0xffff0000, v24
	v_pk_mul_f32 v[22:23], v[22:23], v[26:27]
	v_lshlrev_b32_e32 v24, 16, v25
	v_cvt_pk_bf16_f32 v20, v22, v23
	v_lshlrev_b32_e32 v22, 16, v21
	v_and_b32_e32 v23, 0xffff0000, v21
	v_and_b32_e32 v25, 0xffff0000, v25
	v_pk_mul_f32 v[22:23], v[22:23], v[24:25]
	s_nop 0
	v_cvt_pk_bf16_f32 v21, v22, v23
	global_store_dwordx4 v[38:39], v[18:21], off
	s_waitcnt vmcnt(7)
; #define LAS __attribute__((address_space(3)))
; __device__ __forceinline__ unsigned cvt_pk_bf16(float lo, float hi) { f32x2 v = {lo, hi}; bf16x2_t b = __builtin_convertvector(v, bf16x2_t); return __builtin_bit_cast(unsigned, b); }
; __device__ __forceinline__ float bf_lo(unsigned u) { return __uint_as_float(u << 16); }
; __device__ __forceinline__ float bf_hi(unsigned u) { return __uint_as_float(u & 0xffff0000u); }
; __device__ __forceinline__ void phase_spatial(const Args& a, LAS unsigned char* lds, int j, int nchunks) {
;     ...
;           for (int p8 = 0; p8 < 8; ++p8) { const int row = lrow + 16 * p8; uu[p8] = *(const u32x4*)(Z + (row0 + row) * SGUW + g * 256 + lch * 8); }
; #pragma unroll
;           for (int p8 = 0; p8 < 8; ++p8) { const int row = lrow + 16 * p8; const u32x2 s0 = *(const LAS u32x2*)(vt + row * 520 + lch * 16), s1 = *(const LAS u32x2*)(vt + row * 520 + lch * 16 + 8);
;               u32x4 o; o.x = cvt_pk_bf16(bf_lo(uu[p8].x) * bf_lo(s0.x), bf_hi(uu[p8].x) * bf_hi(s0.x)); o.y = cvt_pk_bf16(bf_lo(uu[p8].y) * bf_lo(s0.y), bf_hi(uu[p8].y) * bf_hi(s0.y));
;               o.z = cvt_pk_bf16(bf_lo(uu[p8].z) * bf_lo(s1.x), bf_hi(uu[p8].z) * bf_hi(s1.x)); o.w = cvt_pk_bf16(bf_lo(uu[p8].w) * bf_lo(s1.y), bf_hi(uu[p8].w) * bf_hi(s1.y));
;               *(u32x4*)(Z + (row0 + row) * SGUW + g * 256 + lch * 8) = o; } }
;         __syncthreads();
	v_lshlrev_b32_e32 v22, 16, v14
	v_and_b32_e32 v23, 0xffff0000, v14
	v_add_u32_e32 v18, 0x6180, v146
	ds_read2_b64 v[18:21], v18 offset1:1
	s_waitcnt lgkmcnt(0)
	v_lshlrev_b32_e32 v24, 16, v18
	v_and_b32_e32 v25, 0xffff0000, v18
	v_pk_mul_f32 v[22:23], v[22:23], v[24:25]
	v_lshlrev_b32_e32 v18, 16, v19
	v_cvt_pk_bf16_f32 v14, v22, v23
	v_lshlrev_b32_e32 v22, 16, v15
	v_and_b32_e32 v23, 0xffff0000, v15
	v_and_b32_e32 v19, 0xffff0000, v19
	v_pk_mul_f32 v[18:19], v[22:23], v[18:19]
	v_lshlrev_b32_e32 v22, 16, v20
	v_cvt_pk_bf16_f32 v15, v18, v19
	v_lshlrev_b32_e32 v18, 16, v16
	v_and_b32_e32 v19, 0xffff0000, v16
	v_and_b32_e32 v23, 0xffff0000, v20
	v_pk_mul_f32 v[18:19], v[18:19], v[22:23]
	v_lshlrev_b32_e32 v20, 16, v21
	v_cvt_pk_bf16_f32 v16, v18, v19
	v_lshlrev_b32_e32 v18, 16, v17
	v_and_b32_e32 v19, 0xffff0000, v17
	v_and_b32_e32 v21, 0xffff0000, v21
	v_pk_mul_f32 v[18:19], v[18:19], v[20:21]
	s_nop 0
	v_cvt_pk_bf16_f32 v17, v18, v19
	global_store_dwordx4 v[36:37], v[14:17], off
	s_waitcnt vmcnt(7)
	v_lshlrev_b32_e32 v18, 16, v10
	v_and_b32_e32 v19, 0xffff0000, v10
	v_add_u32_e32 v14, 0x8200, v146
	ds_read2_b64 v[14:17], v14 offset1:1
	s_waitcnt lgkmcnt(0)
	v_lshlrev_b32_e32 v20, 16, v14
	v_and_b32_e32 v21, 0xffff0000, v14
	v_pk_mul_f32 v[18:19], v[18:19], v[20:21]
	v_lshlrev_b32_e32 v14, 16, v15
	v_cvt_pk_bf16_f32 v10, v18, v19
	v_lshlrev_b32_e32 v18, 16, v11
	v_and_b32_e32 v19, 0xffff0000, v11
	v_and_b32_e32 v15, 0xffff0000, v15
	v_pk_mul_f32 v[14:15], v[18:19], v[14:15]
	v_lshlrev_b32_e32 v18, 16, v16
	v_cvt_pk_bf16_f32 v11, v14, v15
	v_lshlrev_b32_e32 v14, 16, v12
	v_and_b32_e32 v15, 0xffff0000, v12
	v_and_b32_e32 v19, 0xffff0000, v16
	v_pk_mul_f32 v[14:15], v[14:15], v[18:19]
	v_lshlrev_b32_e32 v16, 16, v17
	v_cvt_pk_bf16_f32 v12, v14, v15
	v_lshlrev_b32_e32 v14, 16, v13
	v_and_b32_e32 v15, 0xffff0000, v13
	v_and_b32_e32 v17, 0xffff0000, v17
	v_pk_mul_f32 v[14:15], v[14:15], v[16:17]
	s_nop 0
	v_cvt_pk_bf16_f32 v13, v14, v15
	global_store_dwordx4 v[34:35], v[10:13], off
	s_waitcnt vmcnt(7)
	v_lshlrev_b32_e32 v14, 16, v6
	v_and_b32_e32 v15, 0xffff0000, v6
	v_add_u32_e32 v10, 0xa280, v146
	ds_read2_b64 v[10:13], v10 offset1:1
	s_waitcnt lgkmcnt(0)
	v_lshlrev_b32_e32 v16, 16, v10
	v_and_b32_e32 v17, 0xffff0000, v10
	v_pk_mul_f32 v[14:15], v[14:15], v[16:17]
	v_lshlrev_b32_e32 v10, 16, v11
	v_cvt_pk_bf16_f32 v6, v14, v15
	v_lshlrev_b32_e32 v14, 16, v7
	v_and_b32_e32 v15, 0xffff0000, v7
	v_and_b32_e32 v11, 0xffff0000, v11
	v_pk_mul_f32 v[10:11], v[14:15], v[10:11]
	v_lshlrev_b32_e32 v14, 16, v12
	v_cvt_pk_bf16_f32 v7, v10, v11
	v_lshlrev_b32_e32 v10, 16, v8
	v_and_b32_e32 v11, 0xffff0000, v8
	v_and_b32_e32 v15, 0xffff0000, v12
	v_pk_mul_f32 v[10:11], v[10:11], v[14:15]
	v_lshlrev_b32_e32 v12, 16, v13
	v_cvt_pk_bf16_f32 v8, v10, v11
	v_lshlrev_b32_e32 v10, 16, v9
	v_and_b32_e32 v11, 0xffff0000, v9
	v_and_b32_e32 v13, 0xffff0000, v13
	v_pk_mul_f32 v[10:11], v[10:11], v[12:13]
	s_nop 0
	v_cvt_pk_bf16_f32 v9, v10, v11
	global_store_dwordx4 v[32:33], v[6:9], off
	s_waitcnt vmcnt(7)
	v_lshlrev_b32_e32 v10, 16, v2
	v_and_b32_e32 v11, 0xffff0000, v2
	v_add_u32_e32 v6, 0xc300, v146
	ds_read2_b64 v[6:9], v6 offset1:1
	s_waitcnt lgkmcnt(0)
	v_lshlrev_b32_e32 v12, 16, v6
	v_and_b32_e32 v13, 0xffff0000, v6
	v_pk_mul_f32 v[10:11], v[10:11], v[12:13]
	v_lshlrev_b32_e32 v6, 16, v7
	v_cvt_pk_bf16_f32 v2, v10, v11
	v_lshlrev_b32_e32 v10, 16, v3
	v_and_b32_e32 v11, 0xffff0000, v3
	v_and_b32_e32 v7, 0xffff0000, v7
	v_pk_mul_f32 v[6:7], v[10:11], v[6:7]
	v_lshlrev_b32_e32 v10, 16, v8
	v_cvt_pk_bf16_f32 v3, v6, v7
	v_lshlrev_b32_e32 v6, 16, v4
	v_and_b32_e32 v7, 0xffff0000, v4
	v_and_b32_e32 v11, 0xffff0000, v8
	v_pk_mul_f32 v[6:7], v[6:7], v[10:11]
	v_lshlrev_b32_e32 v8, 16, v9
	v_cvt_pk_bf16_f32 v4, v6, v7
	v_lshlrev_b32_e32 v6, 16, v5
	v_and_b32_e32 v7, 0xffff0000, v5
	v_and_b32_e32 v9, 0xffff0000, v9
	v_pk_mul_f32 v[6:7], v[6:7], v[8:9]
	s_nop 0
	v_cvt_pk_bf16_f32 v5, v6, v7
	global_store_dwordx4 v[30:31], v[2:5], off
	s_barrier
	s_cbranch_scc1 .LBB0_254
